# attention tile loop unrolled by two: LDS double-buffer parity is a compile-time constant, per-tile LDS address arithmetic (6 VALU + 8 SALU) replaced by immediate offsets and precomputed bases
# speedup vs baseline: 1.0024x; 1.0001x over previous
; #define FL_GLOADK(j) do { \
;     _Pragma("unroll") for (int i_ = 0; i_ < KPT; ++i_) { const int ci = tid + 512 * i_; if (ci < NKC) { const int key = ci / KCH, ch = ci - key * KCH; \
;         kreg[i_] = *(const u32x4*)(K0 + (size_t)(64 * (j) + key) * kpitch + ch * 8); } } } while (0)
; #define FL_LSTOREK(buf) do { \
;     _Pragma("unroll") for (int i_ = 0; i_ < KPT; ++i_) { const int ci = tid + 512 * i_; if (ci < NKC) { const int key = ci / KCH, ch = ci - key * KCH; \
;         *(LAS u32x4*)(lds + (buf) * KB + (key * KP + ch * 8) * 2) = kreg[i_]; } } } while (0)
; #define FL_GLOADV(j) do { \
;     _Pragma("unroll") for (int i_ = 0; i_ < VPT; ++i_) { const int ci = tid + 512 * i_; const int d = ci >> 3, ch = ci & 7; kreg[i_] = *(const u32x4*)(VT + (size_t)d * vpitch + 64 * (j) + ch * 8); } } while (0)
; #define FL_LSTOREV(buf) do { \
;     _Pragma("unroll") for (int i_ = 0; i_ < VPT; ++i_) { const int ci = tid + 512 * i_; const int d = ci >> 3, ch = ci & 7; LAS u32x2* p_ = (LAS u32x2*)(lds + 2 * KB + (buf) * VB + (d * VP + ch * 8) * 2); \
;         p_[0] = (u32x2){kreg[i_].x, kreg[i_].y}; p_[1] = (u32x2){kreg[i_].z, kreg[i_].w}; } } while (0)
; template <int DQK, int DV, int MODE>
; __device__ __forceinline__ void flash_unit(LAS unsigned char* lds, const bf16* Qp, int qpitch, const bf16* K0, int kpitch, const bf16* K1, const bf16* VT, int vpitch,
;                                            bf16* Op, int opitch, int NT, int jbase, int qpos0) {
;     ...
;     for (int j = 0; j < NT; ++j) {
;         const int buf = j & 1;
;         if (j + 1 < NT) { if constexpr (MODE == 1) { FL_GLOADK(j + 1); FL_LSTOREK(buf ^ 1); FL_GLOADV(j + 1); FL_LSTOREV(buf ^ 1); } else { FL_GLOAD(j + 1); } }
;         if (MODE == 1 || j <= jmax) { FL_X(j); FL_Y(j); }
;         if constexpr (MODE == 0) { if (j + 1 < NT) { FL_LSTORE(buf ^ 1); } }
;         __syncthreads();
.LBB0_548:
	s_or_b64 exec, exec, s[6:7]
	v_add_u32_e32 v160, v90, v87
	v_mad_u64_u32 v[2:3], s[6:7], v160, -12, v[84:85]
	v_add_u32_e32 v0, 0x8a00, v155
	v_lshlrev_b32_e32 v4, 3, v2
	v_mad_u64_u32 v[8:9], s[6:7], v14, -12, v[86:87]
	s_waitcnt vmcnt(0) lgkmcnt(0)
	ds_write2_b64 v0, v[64:65], v[66:67] offset1:1
	v_ashrrev_i32_e32 v5, 31, v4
	v_subrev_u32_e32 v0, 64, v4
	v_lshlrev_b32_e32 v10, 3, v8
	v_lshl_add_u64 v[6:7], v[4:5], 1, s[14:15]
	v_lshl_add_u64 v[4:5], v[0:1], 1, s[16:17]
	v_ashrrev_i32_e32 v11, 31, v10
	v_subrev_u32_e32 v0, 64, v10
	v_lshl_add_u64 v[12:13], v[10:11], 1, s[14:15]
	v_lshl_add_u64 v[10:11], v[0:1], 1, s[16:17]
	v_and_b32_e32 v0, 7, v85
	v_cmp_lt_i32_e32 vcc, 7, v2
	v_lshlrev_b32_e32 v0, 4, v0
	v_lshlrev_b32_e32 v178, 4, v2
	v_cndmask_b32_e32 v167, v7, v5, vcc
	v_cndmask_b32_e32 v166, v6, v4, vcc
	v_cndmask_b32_e64 v168, 10, 6, vcc
	v_cmp_lt_i32_e32 vcc, 7, v8
	v_ashrrev_i32_e32 v161, 31, v160
	v_ashrrev_i32_e32 v15, 31, v14
	v_lshl_add_u64 v[2:3], v[88:89], 0, v[0:1]
	v_mul_lo_u32 v179, v160, s49
	v_cndmask_b32_e32 v163, v13, v11, vcc
	v_cndmask_b32_e32 v162, v12, v10, vcc
	v_cndmask_b32_e64 v164, 10, 6, vcc
	v_lshl_add_u64 v[170:171], v[160:161], 0, s[10:11]
	v_lshl_add_u64 v[172:173], v[14:15], 0, s[10:11]
	v_lshl_add_u64 v[174:175], s[20:21], 0, v[2:3]
	v_lshlrev_b64 v[232:233], v168, v[170:171]
	v_lshl_add_u64 v[232:233], v[166:167], 0, v[232:233]
	v_lshlrev_b64 v[234:235], v164, v[172:173]
	v_lshl_add_u64 v[234:235], v[162:163], 0, v[234:235]
	v_mov_b32_e32 v236, 64
	v_mov_b32_e32 v237, 0
	v_lshlrev_b64 v[238:239], v164, v[236:237]
	v_lshlrev_b64 v[236:237], v168, v[236:237]
	v_add_u32_e32 v240, 0x6800, v155
	v_add_u32_e32 v241, 0x6800, v165
	v_add_u32_e32 v242, 0x7800, v165
	v_add_u32_e32 v243, 0x2200, v241
	v_add_u32_e32 v244, 0x2200, v242
	v_add_u32_e32 v245, v178, v179
	v_add_u32_e32 v246, v176, v177
	v_add_u32_e32 v247, 0x2200, v240
	s_mov_b32 s64, -2
	s_waitcnt lgkmcnt(0)
	s_barrier
	s_branch .Lu1_top

; #define FL_GLOADK(j) do { \
;     _Pragma("unroll") for (int i_ = 0; i_ < KPT; ++i_) { const int ci = tid + 512 * i_; if (ci < NKC) { const int key = ci / KCH, ch = ci - key * KCH; \
;         kreg[i_] = *(const u32x4*)(K0 + (size_t)(64 * (j) + key) * kpitch + ch * 8); } } } while (0)
; #define FL_LSTOREK(buf) do { \
;     _Pragma("unroll") for (int i_ = 0; i_ < KPT; ++i_) { const int ci = tid + 512 * i_; if (ci < NKC) { const int key = ci / KCH, ch = ci - key * KCH; \
;         *(LAS u32x4*)(lds + (buf) * KB + (key * KP + ch * 8) * 2) = kreg[i_]; } } } while (0)
; #define FL_GLOADV(j) do { \
;     _Pragma("unroll") for (int i_ = 0; i_ < VPT; ++i_) { const int ci = tid + 512 * i_; const int d = ci >> 3, ch = ci & 7; kreg[i_] = *(const u32x4*)(VT + (size_t)d * vpitch + 64 * (j) + ch * 8); } } while (0)
; #define FL_LSTOREV(buf) do { \
;     _Pragma("unroll") for (int i_ = 0; i_ < VPT; ++i_) { const int ci = tid + 512 * i_; const int d = ci >> 3, ch = ci & 7; LAS u32x2* p_ = (LAS u32x2*)(lds + 2 * KB + (buf) * VB + (d * VP + ch * 8) * 2); \
;         p_[0] = (u32x2){kreg[i_].x, kreg[i_].y}; p_[1] = (u32x2){kreg[i_].z, kreg[i_].w}; } } while (0)
; template <int DQK, int DV, int MODE>
; __device__ __forceinline__ void flash_unit(LAS unsigned char* lds, const bf16* Qp, int qpitch, const bf16* K0, int kpitch, const bf16* K1, const bf16* VT, int vpitch,
;                                            bf16* Op, int opitch, int NT, int jbase, int qpos0) {
;     ...
;     for (int j = 0; j < NT; ++j) {
;         const int buf = j & 1;
;         if (j + 1 < NT) { if constexpr (MODE == 1) { FL_GLOADK(j + 1); FL_LSTOREK(buf ^ 1); FL_GLOADV(j + 1); FL_LSTOREV(buf ^ 1); } else { FL_GLOAD(j + 1); } }
;         if (MODE == 1 || j <= jmax) { FL_X(j); FL_Y(j); }
.Lu1_554:
	s_or_b64 exec, exec, s[6:7]
	global_load_dwordx4 v[2:5], v[174:175], off
	s_add_i32 s7, s64, 3
	s_cmp_gt_i32 s7, s26
	s_cbranch_scc1 .Lu1_558
	ds_read_b128 v[6:9], v169 offset:13312
	ds_read_b128 v[10:13], v169 offset:13344
	ds_read_b128 v[128:131], v169 offset:19968
	ds_read_b128 v[132:135], v169 offset:20000
	ds_read_b128 v[136:139], v169 offset:13376
	ds_read_b128 v[140:143], v169 offset:13408
	ds_read_b128 v[144:147], v169 offset:20032
	ds_read_b128 v[148:151], v169 offset:20064
	ds_read_b128 v[180:183], v169 offset:13440
	ds_read_b128 v[184:187], v169 offset:13472
	ds_read_b128 v[188:191], v169 offset:20096
	ds_read_b128 v[192:195], v169 offset:20128
	s_waitcnt lgkmcnt(8)
	v_mfma_f32_32x32x16_bf16 v[80:95], v[6:9], v[116:119], v[48:63]
	v_mfma_f32_32x32x16_bf16 v[64:79], v[128:131], v[116:119], v[48:63]
	v_mfma_f32_32x32x16_bf16 v[80:95], v[10:13], v[112:115], v[80:95]
	v_mfma_f32_32x32x16_bf16 v[64:79], v[132:135], v[112:115], v[64:79]
	s_waitcnt lgkmcnt(4)
	v_mfma_f32_32x32x16_bf16 v[80:95], v[136:139], v[108:111], v[80:95]
	v_mfma_f32_32x32x16_bf16 v[64:79], v[144:147], v[108:111], v[64:79]
	v_mfma_f32_32x32x16_bf16 v[80:95], v[140:143], v[104:107], v[80:95]
	v_mfma_f32_32x32x16_bf16 v[64:79], v[148:151], v[104:107], v[64:79]
	s_waitcnt lgkmcnt(0)
	v_mfma_f32_32x32x16_bf16 v[80:95], v[180:183], v[120:123], v[80:95]
	v_mfma_f32_32x32x16_bf16 v[64:79], v[188:191], v[120:123], v[64:79]
	v_mfma_f32_32x32x16_bf16 v[80:95], v[184:187], v[124:127], v[80:95]
	v_mfma_f32_32x32x16_bf16 v[64:79], v[192:195], v[124:127], v[64:79]
	ds_read2_b64 v[148:151], v243 offset1:2
	ds_read2_b64 v[144:147], v243 offset0:4 offset1:6
	ds_read2_b64 v[140:143], v243 offset0:8 offset1:10
	ds_read2_b64 v[136:139], v243 offset0:12 offset1:14
	ds_read2_b64 v[132:135], v244 offset0:32 offset1:34
	ds_read2_b64 v[128:131], v244 offset0:36 offset1:38
	ds_read2_b64 v[10:13], v244 offset0:40 offset1:42
	ds_read2_b64 v[6:9], v244 offset0:44 offset1:46
	s_nop 2

; template <int DQK, int DV, int MODE>
; __device__ __forceinline__ void flash_unit(LAS unsigned char* lds, const bf16* Qp, int qpitch, const bf16* K0, int kpitch, const bf16* K1, const bf16* VT, int vpitch,
;                                            bf16* Op, int opitch, int NT, int jbase, int qpos0) {
;     ...
;         if constexpr (MODE == 0) { if (j + 1 < NT) { FL_LSTORE(buf ^ 1); } }
;         __syncthreads();
.Lu1_558:
	s_and_saveexec_b64 s[6:7], s[2:3]
	s_cbranch_execz .Lu1_560
	s_waitcnt vmcnt(0) lgkmcnt(0)
	ds_write_b128 v245, v[96:99]
.Lu1_560:
	s_or_b64 exec, exec, s[6:7]
	s_and_saveexec_b64 s[6:7], s[4:5]
	s_cbranch_execz .Lu1_latch
	s_waitcnt vmcnt(0) lgkmcnt(0)
	ds_write_b128 v246, v[100:103]
	s_branch .Lu1_latch
.Lu1_latch:
	s_or_b64 exec, exec, s[6:7]
	s_add_i32 s64, s64, 1
	v_lshl_add_u64 v[232:233], v[232:233], 0, v[236:237]
	v_lshl_add_u64 v[234:235], v[234:235], 0, v[238:239]
	s_cmp_lg_u32 s27, s64
	v_lshl_add_u64 v[174:175], v[174:175], 0, s[10:11]
	s_waitcnt vmcnt(0) lgkmcnt(0)
	ds_write2_b64 v240, v[2:3], v[4:5] offset1:1
	s_waitcnt lgkmcnt(0)
	s_barrier
	s_cbranch_scc0 .LBB0_562

; #define FL_GLOADK(j) do { \
;     _Pragma("unroll") for (int i_ = 0; i_ < KPT; ++i_) { const int ci = tid + 512 * i_; if (ci < NKC) { const int key = ci / KCH, ch = ci - key * KCH; \
;         kreg[i_] = *(const u32x4*)(K0 + (size_t)(64 * (j) + key) * kpitch + ch * 8); } } } while (0)
; #define FL_LSTOREK(buf) do { \
;     _Pragma("unroll") for (int i_ = 0; i_ < KPT; ++i_) { const int ci = tid + 512 * i_; if (ci < NKC) { const int key = ci / KCH, ch = ci - key * KCH; \
;         *(LAS u32x4*)(lds + (buf) * KB + (key * KP + ch * 8) * 2) = kreg[i_]; } } } while (0)
; #define FL_GLOADV(j) do { \
;     _Pragma("unroll") for (int i_ = 0; i_ < VPT; ++i_) { const int ci = tid + 512 * i_; const int d = ci >> 3, ch = ci & 7; kreg[i_] = *(const u32x4*)(VT + (size_t)d * vpitch + 64 * (j) + ch * 8); } } while (0)
; #define FL_LSTOREV(buf) do { \
;     _Pragma("unroll") for (int i_ = 0; i_ < VPT; ++i_) { const int ci = tid + 512 * i_; const int d = ci >> 3, ch = ci & 7; LAS u32x2* p_ = (LAS u32x2*)(lds + 2 * KB + (buf) * VB + (d * VP + ch * 8) * 2); \
;         p_[0] = (u32x2){kreg[i_].x, kreg[i_].y}; p_[1] = (u32x2){kreg[i_].z, kreg[i_].w}; } } while (0)
; template <int DQK, int DV, int MODE>
; __device__ __forceinline__ void flash_unit(LAS unsigned char* lds, const bf16* Qp, int qpitch, const bf16* K0, int kpitch, const bf16* K1, const bf16* VT, int vpitch,
;                                            bf16* Op, int opitch, int NT, int jbase, int qpos0) {
;     ...
;     for (int j = 0; j < NT; ++j) {
;         const int buf = j & 1;
;         if (j + 1 < NT) { if constexpr (MODE == 1) { FL_GLOADK(j + 1); FL_LSTOREK(buf ^ 1); FL_GLOADV(j + 1); FL_LSTOREV(buf ^ 1); } else { FL_GLOAD(j + 1); } }
;         if (MODE == 1 || j <= jmax) { FL_X(j); FL_Y(j); }
.Lu0_554:
	s_or_b64 exec, exec, s[6:7]
	global_load_dwordx4 v[2:5], v[174:175], off
	s_add_i32 s7, s64, 3
	s_cmp_gt_i32 s7, s26
	s_cbranch_scc1 .Lu0_558
	ds_read_b128 v[6:9], v169
	ds_read_b128 v[10:13], v169 offset:32
	ds_read_b128 v[128:131], v169 offset:6656
	ds_read_b128 v[132:135], v169 offset:6688
	ds_read_b128 v[136:139], v169 offset:64
	ds_read_b128 v[140:143], v169 offset:96
	ds_read_b128 v[144:147], v169 offset:6720
	ds_read_b128 v[148:151], v169 offset:6752
	ds_read_b128 v[180:183], v169 offset:128
	ds_read_b128 v[184:187], v169 offset:160
	ds_read_b128 v[188:191], v169 offset:6784
	ds_read_b128 v[192:195], v169 offset:6816
	s_waitcnt lgkmcnt(8)
	v_mfma_f32_32x32x16_bf16 v[80:95], v[6:9], v[116:119], v[48:63]
	v_mfma_f32_32x32x16_bf16 v[64:79], v[128:131], v[116:119], v[48:63]
	v_mfma_f32_32x32x16_bf16 v[80:95], v[10:13], v[112:115], v[80:95]
	v_mfma_f32_32x32x16_bf16 v[64:79], v[132:135], v[112:115], v[64:79]
	s_waitcnt lgkmcnt(4)
	v_mfma_f32_32x32x16_bf16 v[80:95], v[136:139], v[108:111], v[80:95]
	v_mfma_f32_32x32x16_bf16 v[64:79], v[144:147], v[108:111], v[64:79]
	v_mfma_f32_32x32x16_bf16 v[80:95], v[140:143], v[104:107], v[80:95]
	v_mfma_f32_32x32x16_bf16 v[64:79], v[148:151], v[104:107], v[64:79]
	s_waitcnt lgkmcnt(0)
	v_mfma_f32_32x32x16_bf16 v[80:95], v[180:183], v[120:123], v[80:95]
	v_mfma_f32_32x32x16_bf16 v[64:79], v[188:191], v[120:123], v[64:79]
	v_mfma_f32_32x32x16_bf16 v[80:95], v[184:187], v[124:127], v[80:95]
	v_mfma_f32_32x32x16_bf16 v[64:79], v[192:195], v[124:127], v[64:79]
	ds_read2_b64 v[148:151], v241 offset1:2
	ds_read2_b64 v[144:147], v241 offset0:4 offset1:6
	ds_read2_b64 v[140:143], v241 offset0:8 offset1:10
	ds_read2_b64 v[136:139], v241 offset0:12 offset1:14
	ds_read2_b64 v[132:135], v242 offset0:32 offset1:34
	ds_read2_b64 v[128:131], v242 offset0:36 offset1:38
	ds_read2_b64 v[10:13], v242 offset0:40 offset1:42
	ds_read2_b64 v[6:9], v242 offset0:44 offset1:46
	s_nop 2

; template <int DQK, int DV, int MODE>
; __device__ __forceinline__ void flash_unit(LAS unsigned char* lds, const bf16* Qp, int qpitch, const bf16* K0, int kpitch, const bf16* K1, const bf16* VT, int vpitch,
;                                            bf16* Op, int opitch, int NT, int jbase, int qpos0) {
;     ...
;         if constexpr (MODE == 0) { if (j + 1 < NT) { FL_LSTORE(buf ^ 1); } }
;         __syncthreads();
.Lu0_558:
	s_and_saveexec_b64 s[6:7], s[2:3]
	s_cbranch_execz .Lu0_560
	s_waitcnt vmcnt(0) lgkmcnt(0)
	ds_write_b128 v245, v[96:99] offset:13312
.Lu0_560:
	s_or_b64 exec, exec, s[6:7]
	s_and_saveexec_b64 s[6:7], s[4:5]
	s_cbranch_execz .Lu0_latch
	s_waitcnt vmcnt(0) lgkmcnt(0)
	ds_write_b128 v246, v[100:103] offset:13312
	s_branch .Lu0_latch
.Lu0_latch:
	s_or_b64 exec, exec, s[6:7]
	s_add_i32 s64, s64, 1
	v_lshl_add_u64 v[232:233], v[232:233], 0, v[236:237]
	v_lshl_add_u64 v[234:235], v[234:235], 0, v[238:239]
	s_cmp_lg_u32 s27, s64
	v_lshl_add_u64 v[174:175], v[174:175], 0, s[10:11]
	s_waitcnt vmcnt(0) lgkmcnt(0)
	ds_write2_b64 v247, v[2:3], v[4:5] offset1:1
	s_waitcnt lgkmcnt(0)
	s_barrier
	s_cbranch_scc0 .LBB0_562
	s_branch .Lu1_top
.Lu0_slow:
	v_max_f32_e32 v15, v65, v65
	v_max_f32_e32 v161, v64, v64
	v_max_f32_e32 v15, v161, v15
	v_max3_f32 v0, v80, v81, v82
	v_max3_f32 v15, v15, v66, v67
	v_max3_f32 v0, v0, v83, v84
	v_max3_f32 v15, v15, v68, v69
	v_max3_f32 v0, v0, v85, v86
	v_max3_f32 v15, v15, v70, v71
	v_max3_f32 v0, v0, v87, v88
	v_max3_f32 v15, v15, v72, v73
	v_max3_f32 v0, v0, v89, v90
	v_max3_f32 v15, v15, v74, v75
	v_max3_f32 v0, v0, v91, v92
	v_max3_f32 v15, v15, v76, v77
	v_max3_f32 v0, v0, v93, v94
	v_max3_f32 v15, v15, v78, v79
	v_max3_f32 v0, v0, v95, v15
	v_mov_b32_e32 v15, v0
	s_nop 1
	v_permlane32_swap_b32_e32 v0, v15
	v_max_f32_e32 v15, v15, v15
	v_max_f32_e32 v0, v0, v0
	v_max_f32_e32 v0, v0, v15
	v_cmp_lt_f32_e32 vcc, s56, v0
	s_nop 0
	v_cndmask_b32_e32 v0, 0, v0, vcc
	v_exp_f32_e64 v180, -v0
	v_add_f32_e32 v158, v158, v0
	v_xor_b32_e32 v48, 0x80000000, v158
	v_mov_b32_e32 v49, v48
	v_mov_b32_e32 v50, v48
	v_mov_b32_e32 v51, v48
	v_mov_b32_e32 v52, v48
	v_mov_b32_e32 v53, v48
	v_mov_b32_e32 v54, v48
	v_mov_b32_e32 v55, v48
	v_mov_b32_e32 v56, v48
	v_mov_b32_e32 v57, v48
	v_mov_b32_e32 v58, v48
	v_mov_b32_e32 v59, v48
	v_mov_b32_e32 v60, v48
	v_mov_b32_e32 v61, v48
	v_mov_b32_e32 v62, v48
	v_mov_b32_e32 v63, v48
	v_pk_add_f32 v[80:81], v[80:81], v[0:1] op_sel_hi:[1,0] neg_lo:[0,1] neg_hi:[0,1]
	v_pk_add_f32 v[64:65], v[64:65], v[0:1] op_sel_hi:[1,0] neg_lo:[0,1] neg_hi:[0,1]
	v_pk_add_f32 v[82:83], v[82:83], v[0:1] op_sel_hi:[1,0] neg_lo:[0,1] neg_hi:[0,1]
	v_pk_add_f32 v[66:67], v[66:67], v[0:1] op_sel_hi:[1,0] neg_lo:[0,1] neg_hi:[0,1]
	v_pk_add_f32 v[84:85], v[84:85], v[0:1] op_sel_hi:[1,0] neg_lo:[0,1] neg_hi:[0,1]
	v_pk_add_f32 v[68:69], v[68:69], v[0:1] op_sel_hi:[1,0] neg_lo:[0,1] neg_hi:[0,1]
	v_pk_add_f32 v[86:87], v[86:87], v[0:1] op_sel_hi:[1,0] neg_lo:[0,1] neg_hi:[0,1]
	v_pk_add_f32 v[70:71], v[70:71], v[0:1] op_sel_hi:[1,0] neg_lo:[0,1] neg_hi:[0,1]
	v_pk_add_f32 v[88:89], v[88:89], v[0:1] op_sel_hi:[1,0] neg_lo:[0,1] neg_hi:[0,1]
	v_pk_add_f32 v[72:73], v[72:73], v[0:1] op_sel_hi:[1,0] neg_lo:[0,1] neg_hi:[0,1]
	v_pk_add_f32 v[90:91], v[90:91], v[0:1] op_sel_hi:[1,0] neg_lo:[0,1] neg_hi:[0,1]
	v_pk_add_f32 v[74:75], v[74:75], v[0:1] op_sel_hi:[1,0] neg_lo:[0,1] neg_hi:[0,1]
	v_pk_add_f32 v[92:93], v[92:93], v[0:1] op_sel_hi:[1,0] neg_lo:[0,1] neg_hi:[0,1]
	v_pk_add_f32 v[76:77], v[76:77], v[0:1] op_sel_hi:[1,0] neg_lo:[0,1] neg_hi:[0,1]
	v_pk_add_f32 v[94:95], v[94:95], v[0:1] op_sel_hi:[1,0] neg_lo:[0,1] neg_hi:[0,1]
	v_pk_add_f32 v[78:79], v[78:79], v[0:1] op_sel_hi:[1,0] neg_lo:[0,1] neg_hi:[0,1]
	v_pk_mul_f32 v[46:47], v[46:47], v[180:181] op_sel_hi:[1,0]
	v_pk_mul_f32 v[44:45], v[44:45], v[180:181] op_sel_hi:[1,0]
	v_pk_mul_f32 v[42:43], v[42:43], v[180:181] op_sel_hi:[1,0]
	v_pk_mul_f32 v[40:41], v[40:41], v[180:181] op_sel_hi:[1,0]
	v_pk_mul_f32 v[38:39], v[38:39], v[180:181] op_sel_hi:[1,0]
	v_pk_mul_f32 v[36:37], v[36:37], v[180:181] op_sel_hi:[1,0]
	v_pk_mul_f32 v[34:35], v[34:35], v[180:181] op_sel_hi:[1,0]
	v_pk_mul_f32 v[32:33], v[32:33], v[180:181] op_sel_hi:[1,0]
	v_pk_mul_f32 v[30:31], v[30:31], v[180:181] op_sel_hi:[1,0]
	v_pk_mul_f32 v[28:29], v[28:29], v[180:181] op_sel_hi:[1,0]
	v_pk_mul_f32 v[26:27], v[26:27], v[180:181] op_sel_hi:[1,0]
	v_pk_mul_f32 v[24:25], v[24:25], v[180:181] op_sel_hi:[1,0]
	v_pk_mul_f32 v[22:23], v[22:23], v[180:181] op_sel_hi:[1,0]
	v_pk_mul_f32 v[20:21], v[20:21], v[180:181] op_sel_hi:[1,0]
	v_pk_mul_f32 v[18:19], v[18:19], v[180:181] op_sel_hi:[1,0]
	v_pk_mul_f32 v[16:17], v[16:17], v[180:181] op_sel_hi:[1,0]
	v_mul_f32_e32 v159, v159, v180
	s_branch .Lu0_557
.Lu1_slow:
	v_max_f32_e32 v15, v65, v65
	v_max_f32_e32 v161, v64, v64
	v_max_f32_e32 v15, v161, v15
	v_max3_f32 v0, v80, v81, v82
	v_max3_f32 v15, v15, v66, v67
	v_max3_f32 v0, v0, v83, v84
	v_max3_f32 v15, v15, v68, v69
	v_max3_f32 v0, v0, v85, v86
	v_max3_f32 v15, v15, v70, v71
	v_max3_f32 v0, v0, v87, v88
	v_max3_f32 v15, v15, v72, v73
	v_max3_f32 v0, v0, v89, v90
	v_max3_f32 v15, v15, v74, v75
	v_max3_f32 v0, v0, v91, v92
	v_max3_f32 v15, v15, v76, v77
	v_max3_f32 v0, v0, v93, v94
	v_max3_f32 v15, v15, v78, v79
	v_max3_f32 v0, v0, v95, v15
	v_mov_b32_e32 v15, v0
	s_nop 1
	v_permlane32_swap_b32_e32 v0, v15
	v_max_f32_e32 v15, v15, v15
	v_max_f32_e32 v0, v0, v0
	v_max_f32_e32 v0, v0, v15
	v_cmp_lt_f32_e32 vcc, s56, v0
	s_nop 0
	v_cndmask_b32_e32 v0, 0, v0, vcc
	v_exp_f32_e64 v180, -v0
	v_add_f32_e32 v158, v158, v0
	v_xor_b32_e32 v48, 0x80000000, v158
	v_mov_b32_e32 v49, v48
	v_mov_b32_e32 v50, v48
	v_mov_b32_e32 v51, v48
	v_mov_b32_e32 v52, v48
	v_mov_b32_e32 v53, v48
	v_mov_b32_e32 v54, v48
	v_mov_b32_e32 v55, v48
	v_mov_b32_e32 v56, v48
	v_mov_b32_e32 v57, v48
	v_mov_b32_e32 v58, v48
	v_mov_b32_e32 v59, v48
	v_mov_b32_e32 v60, v48
	v_mov_b32_e32 v61, v48
	v_mov_b32_e32 v62, v48
	v_mov_b32_e32 v63, v48
	v_pk_add_f32 v[80:81], v[80:81], v[0:1] op_sel_hi:[1,0] neg_lo:[0,1] neg_hi:[0,1]
	v_pk_add_f32 v[64:65], v[64:65], v[0:1] op_sel_hi:[1,0] neg_lo:[0,1] neg_hi:[0,1]
	v_pk_add_f32 v[82:83], v[82:83], v[0:1] op_sel_hi:[1,0] neg_lo:[0,1] neg_hi:[0,1]
	v_pk_add_f32 v[66:67], v[66:67], v[0:1] op_sel_hi:[1,0] neg_lo:[0,1] neg_hi:[0,1]
	v_pk_add_f32 v[84:85], v[84:85], v[0:1] op_sel_hi:[1,0] neg_lo:[0,1] neg_hi:[0,1]
	v_pk_add_f32 v[68:69], v[68:69], v[0:1] op_sel_hi:[1,0] neg_lo:[0,1] neg_hi:[0,1]
	v_pk_add_f32 v[86:87], v[86:87], v[0:1] op_sel_hi:[1,0] neg_lo:[0,1] neg_hi:[0,1]
	v_pk_add_f32 v[70:71], v[70:71], v[0:1] op_sel_hi:[1,0] neg_lo:[0,1] neg_hi:[0,1]
	v_pk_add_f32 v[88:89], v[88:89], v[0:1] op_sel_hi:[1,0] neg_lo:[0,1] neg_hi:[0,1]
	v_pk_add_f32 v[72:73], v[72:73], v[0:1] op_sel_hi:[1,0] neg_lo:[0,1] neg_hi:[0,1]
	v_pk_add_f32 v[90:91], v[90:91], v[0:1] op_sel_hi:[1,0] neg_lo:[0,1] neg_hi:[0,1]
	v_pk_add_f32 v[74:75], v[74:75], v[0:1] op_sel_hi:[1,0] neg_lo:[0,1] neg_hi:[0,1]
	v_pk_add_f32 v[92:93], v[92:93], v[0:1] op_sel_hi:[1,0] neg_lo:[0,1] neg_hi:[0,1]
	v_pk_add_f32 v[76:77], v[76:77], v[0:1] op_sel_hi:[1,0] neg_lo:[0,1] neg_hi:[0,1]
	v_pk_add_f32 v[94:95], v[94:95], v[0:1] op_sel_hi:[1,0] neg_lo:[0,1] neg_hi:[0,1]
	v_pk_add_f32 v[78:79], v[78:79], v[0:1] op_sel_hi:[1,0] neg_lo:[0,1] neg_hi:[0,1]
	v_pk_mul_f32 v[46:47], v[46:47], v[180:181] op_sel_hi:[1,0]
	v_pk_mul_f32 v[44:45], v[44:45], v[180:181] op_sel_hi:[1,0]
	v_pk_mul_f32 v[42:43], v[42:43], v[180:181] op_sel_hi:[1,0]
	v_pk_mul_f32 v[40:41], v[40:41], v[180:181] op_sel_hi:[1,0]
	v_pk_mul_f32 v[38:39], v[38:39], v[180:181] op_sel_hi:[1,0]
	v_pk_mul_f32 v[36:37], v[36:37], v[180:181] op_sel_hi:[1,0]
	v_pk_mul_f32 v[34:35], v[34:35], v[180:181] op_sel_hi:[1,0]
	v_pk_mul_f32 v[32:33], v[32:33], v[180:181] op_sel_hi:[1,0]
	v_pk_mul_f32 v[30:31], v[30:31], v[180:181] op_sel_hi:[1,0]
	v_pk_mul_f32 v[28:29], v[28:29], v[180:181] op_sel_hi:[1,0]
	v_pk_mul_f32 v[26:27], v[26:27], v[180:181] op_sel_hi:[1,0]
	v_pk_mul_f32 v[24:25], v[24:25], v[180:181] op_sel_hi:[1,0]
	v_pk_mul_f32 v[22:23], v[22:23], v[180:181] op_sel_hi:[1,0]
	v_pk_mul_f32 v[20:21], v[20:21], v[180:181] op_sel_hi:[1,0]
	v_pk_mul_f32 v[18:19], v[18:19], v[180:181] op_sel_hi:[1,0]
	v_pk_mul_f32 v[16:17], v[16:17], v[180:181] op_sel_hi:[1,0]
	v_mul_f32_e32 v159, v159, v180
	s_branch .Lu1_557
